# fast attention loop: dropped redundant QK-side lgkmcnt waits, m0 save/restore in LDS-DMA blocks, +0.0 add
# speedup vs baseline: 1.0434x; 1.0037x over previous
.Lattn_fast_top:
	v_add_u32_e32 v185, s20, v224
	ds_read_b64_tr_b16 v[176:177], v185 offset:24576
	ds_read_b64_tr_b16 v[178:179], v185 offset:25088
	v_mfma_f32_32x32x16_bf16 v[96:111], v[80:83], v[156:159], v[32:47]
	v_add_f32_e32 v84, v64, v65
	v_add_f32_e32 v84, v66, v84
	v_add_f32_e32 v84, v67, v84
	v_add_f32_e32 v84, v68, v84
	v_add_f32_e32 v84, v69, v84
	v_cvt_pk_bf16_f32 v148, v64, v65
	v_cvt_pk_bf16_f32 v149, v66, v67
	ds_read_b64_tr_b16 v[172:173], v185 offset:28672
	ds_read_b64_tr_b16 v[174:175], v185 offset:29184
	v_add_f32_e32 v64, v70, v84
	v_mfma_f32_32x32x16_bf16 v[80:95], v[164:167], v[156:159], v[32:47]
	v_add_f32_e32 v64, v71, v64
	v_add_f32_e32 v64, v72, v64
	v_add_f32_e32 v128, v73, v64
	v_cvt_pk_bf16_f32 v150, v68, v69
	v_cvt_pk_bf16_f32 v151, v70, v71
	ds_read_b64_tr_b16 v[64:65], v185 offset:25600
	ds_read_b64_tr_b16 v[66:67], v185 offset:26112
	v_mfma_f32_32x32x16_bf16 v[96:111], v[168:171], v[152:155], v[96:111]
	v_add_f32_e32 v68, v74, v128
	v_add_f32_e32 v68, v75, v68
	v_add_f32_e32 v68, v76, v68
	v_add_f32_e32 v128, v77, v68
	v_cvt_pk_bf16_f32 v144, v72, v73
	v_cvt_pk_bf16_f32 v145, v74, v75
	ds_read_b64_tr_b16 v[68:69], v185 offset:29696
	ds_read_b64_tr_b16 v[70:71], v185 offset:30208
	v_mfma_f32_32x32x16_bf16 v[80:95], v[160:163], v[152:155], v[80:95]
	v_add_f32_e32 v72, v78, v128
	v_add_f32_e32 v72, v79, v72
	v_add_f32_e32 v72, v48, v72
	v_add_f32_e32 v128, v49, v72
	v_cvt_pk_bf16_f32 v146, v76, v77
	v_cvt_pk_bf16_f32 v147, v78, v79
	ds_read_b64_tr_b16 v[72:73], v185 offset:26624
	ds_read_b64_tr_b16 v[74:75], v185 offset:27136
	v_mfma_f32_32x32x16_bf16 v[96:111], v[124:127], v[140:143], v[96:111]
	v_add_f32_e32 v76, v50, v128
	v_add_f32_e32 v76, v51, v76
	v_add_f32_e32 v76, v52, v76
	v_add_f32_e32 v76, v53, v76
	v_cvt_pk_bf16_f32 v136, v48, v49
	v_cvt_pk_bf16_f32 v137, v50, v51
	ds_read_b64_tr_b16 v[48:49], v185 offset:30720
	ds_read_b64_tr_b16 v[50:51], v185 offset:31232
	v_mfma_f32_32x32x16_bf16 v[80:95], v[120:123], v[140:143], v[80:95]
	v_add_f32_e32 v76, v54, v76
	v_add_f32_e32 v76, v55, v76
	v_add_f32_e32 v76, v56, v76
	v_add_f32_e32 v76, v57, v76
	v_cvt_pk_bf16_f32 v138, v52, v53
	v_cvt_pk_bf16_f32 v139, v54, v55
	ds_read_b64_tr_b16 v[52:53], v185 offset:27648
	ds_read_b64_tr_b16 v[54:55], v185 offset:28160
	v_mfma_f32_32x32x16_bf16 v[96:111], v[116:119], v[132:135], v[96:111]
	v_add_f32_e32 v76, v58, v76
	v_add_f32_e32 v76, v59, v76
	v_add_f32_e32 v76, v60, v76
	v_add_f32_e32 v76, v61, v76
	v_cvt_pk_bf16_f32 v128, v56, v57
	v_cvt_pk_bf16_f32 v129, v58, v59
	ds_read_b64_tr_b16 v[56:57], v185 offset:31744
	ds_read_b64_tr_b16 v[58:59], v185 offset:32256
	v_mfma_f32_32x32x16_bf16 v[80:95], v[112:115], v[132:135], v[80:95]
	v_add_f32_e32 v76, v62, v76
	v_add_f32_e32 v76, v63, v76
	v_cvt_pk_bf16_f32 v130, v60, v61
	v_cvt_pk_bf16_f32 v131, v62, v63
	s_mov_b64 s[20:21], 0x6000
	v_lshl_add_u64 v[60:61], v[180:181], 0, s[20:21]
	s_add_i32 m0, s43, s39
	s_nop 0
	global_load_lds_dwordx4 v[60:61], off
	v_lshl_add_u64 v[60:61], v[182:183], 0, s[48:49]
	s_add_i32 m0, s42, s35
	s_nop 0
	global_load_lds_dwordx4 v[60:61], off
	v_add_f32_e32 v184, v184, v76
	s_waitcnt lgkmcnt(14)
	v_mfma_f32_32x32x16_bf16 v[0:15], v[148:151], v[176:179], v[0:15]
	v_exp_f32_e32 v96, v96
	v_exp_f32_e32 v97, v97
	v_exp_f32_e32 v98, v98
	v_exp_f32_e32 v99, v99
	s_waitcnt lgkmcnt(12)
	v_mfma_f32_32x32x16_bf16 v[16:31], v[148:151], v[172:175], v[16:31]
	v_exp_f32_e32 v100, v100
	v_exp_f32_e32 v101, v101
	v_exp_f32_e32 v102, v102
	v_exp_f32_e32 v103, v103
	v_add_u32_e32 v76, s42, v225
	ds_read_b128 v[60:63], v76
	ds_read_b128 v[172:175], v76 offset:512
	s_waitcnt lgkmcnt(12)
	v_mfma_f32_32x32x16_bf16 v[0:15], v[144:147], v[64:67], v[0:15]
	v_exp_f32_e32 v104, v104
	v_exp_f32_e32 v105, v105
	v_exp_f32_e32 v106, v106
	v_exp_f32_e32 v107, v107
	ds_read_b128 v[176:179], v76 offset:2048
	ds_read_b128 v[168:171], v76 offset:2560
	s_waitcnt lgkmcnt(12)
	v_mfma_f32_32x32x16_bf16 v[16:31], v[144:147], v[68:71], v[16:31]
	v_exp_f32_e32 v108, v108
	v_exp_f32_e32 v109, v109
	v_exp_f32_e32 v110, v110
	v_exp_f32_e32 v111, v111
	ds_read_b128 v[164:167], v76 offset:4096
	ds_read_b128 v[160:163], v76 offset:4608
	s_waitcnt lgkmcnt(12)
	v_mfma_f32_32x32x16_bf16 v[0:15], v[136:139], v[72:75], v[0:15]
	v_exp_f32_e32 v80, v80
	v_exp_f32_e32 v81, v81
	v_exp_f32_e32 v82, v82
	v_exp_f32_e32 v83, v83
	ds_read_b128 v[124:127], v76 offset:6144
	ds_read_b128 v[120:123], v76 offset:6656
	s_waitcnt lgkmcnt(12)
	v_mfma_f32_32x32x16_bf16 v[16:31], v[136:139], v[48:51], v[16:31]
	v_exp_f32_e32 v84, v84
	v_exp_f32_e32 v85, v85
	v_exp_f32_e32 v86, v86
	v_exp_f32_e32 v87, v87
	s_waitcnt lgkmcnt(10)
	v_mfma_f32_32x32x16_bf16 v[0:15], v[128:131], v[52:55], v[0:15]
	v_exp_f32_e32 v88, v88
	v_exp_f32_e32 v89, v89
	v_exp_f32_e32 v90, v90
	v_exp_f32_e32 v91, v91
	s_waitcnt lgkmcnt(8)
	v_mfma_f32_32x32x16_bf16 v[16:31], v[128:131], v[56:59], v[16:31]
	v_exp_f32_e32 v92, v92
	v_exp_f32_e32 v93, v93
	v_exp_f32_e32 v94, v94
	v_exp_f32_e32 v95, v95
	s_waitcnt vmcnt(2) lgkmcnt(0)
	s_barrier
	s_add_i32 s20, s42, 0x2000
	s_cmpk_lg_i32 s42, 0x4000
	s_cselect_b32 s44, s20, 0
	v_add_u32_e32 v185, s43, v224
	ds_read_b64_tr_b16 v[116:117], v185 offset:24576
	ds_read_b64_tr_b16 v[118:119], v185 offset:25088
	v_mfma_f32_32x32x16_bf16 v[64:79], v[60:63], v[156:159], v[32:47]
	v_add_f32_e32 v48, v96, v97
	v_add_f32_e32 v48, v98, v48
	v_add_f32_e32 v48, v99, v48
	v_add_f32_e32 v48, v100, v48
	v_add_f32_e32 v48, v101, v48
	v_cvt_pk_bf16_f32 v148, v96, v97
	v_cvt_pk_bf16_f32 v149, v98, v99
	ds_read_b64_tr_b16 v[112:113], v185 offset:28672
	ds_read_b64_tr_b16 v[114:115], v185 offset:29184
	v_add_f32_e32 v48, v102, v48
	v_add_f32_e32 v48, v103, v48
	v_add_f32_e32 v48, v104, v48
	v_add_f32_e32 v128, v105, v48
	v_mfma_f32_32x32x16_bf16 v[48:63], v[172:175], v[156:159], v[32:47]
	v_cvt_pk_bf16_f32 v150, v100, v101
	v_cvt_pk_bf16_f32 v151, v102, v103
	ds_read_b64_tr_b16 v[96:97], v185 offset:25600
	ds_read_b64_tr_b16 v[98:99], v185 offset:26112
	v_mfma_f32_32x32x16_bf16 v[64:79], v[176:179], v[152:155], v[64:79]
	v_add_f32_e32 v100, v106, v128
	v_add_f32_e32 v100, v107, v100
	v_add_f32_e32 v100, v108, v100
	v_add_f32_e32 v128, v109, v100
	v_cvt_pk_bf16_f32 v144, v104, v105
	v_cvt_pk_bf16_f32 v145, v106, v107
	ds_read_b64_tr_b16 v[100:101], v185 offset:29696
	ds_read_b64_tr_b16 v[102:103], v185 offset:30208
	v_mfma_f32_32x32x16_bf16 v[48:63], v[168:171], v[152:155], v[48:63]
	v_add_f32_e32 v104, v110, v128
	v_add_f32_e32 v104, v111, v104
	v_add_f32_e32 v104, v80, v104
	v_add_f32_e32 v128, v81, v104
	v_cvt_pk_bf16_f32 v146, v108, v109
	v_cvt_pk_bf16_f32 v147, v110, v111
	ds_read_b64_tr_b16 v[104:105], v185 offset:26624
	ds_read_b64_tr_b16 v[106:107], v185 offset:27136
	v_mfma_f32_32x32x16_bf16 v[64:79], v[164:167], v[140:143], v[64:79]
	v_add_f32_e32 v108, v82, v128
	v_add_f32_e32 v108, v83, v108
	v_add_f32_e32 v108, v84, v108
	v_add_f32_e32 v128, v85, v108
	v_cvt_pk_bf16_f32 v136, v80, v81
	v_cvt_pk_bf16_f32 v137, v82, v83
	ds_read_b64_tr_b16 v[108:109], v185 offset:30720
	ds_read_b64_tr_b16 v[110:111], v185 offset:31232
	v_mfma_f32_32x32x16_bf16 v[48:63], v[160:163], v[140:143], v[48:63]
	v_add_f32_e32 v80, v86, v128
	v_add_f32_e32 v80, v87, v80
	v_add_f32_e32 v80, v88, v80
	v_add_f32_e32 v80, v89, v80
	v_cvt_pk_bf16_f32 v138, v84, v85
	v_cvt_pk_bf16_f32 v139, v86, v87
	ds_read_b64_tr_b16 v[84:85], v185 offset:27648
	ds_read_b64_tr_b16 v[86:87], v185 offset:28160
	v_mfma_f32_32x32x16_bf16 v[64:79], v[124:127], v[132:135], v[64:79]
	v_add_f32_e32 v80, v90, v80
	v_add_f32_e32 v80, v91, v80
	v_add_f32_e32 v80, v92, v80
	v_add_f32_e32 v80, v93, v80
	v_cvt_pk_bf16_f32 v128, v88, v89
	v_cvt_pk_bf16_f32 v129, v90, v91
	ds_read_b64_tr_b16 v[88:89], v185 offset:31744
	ds_read_b64_tr_b16 v[90:91], v185 offset:32256
	v_mfma_f32_32x32x16_bf16 v[48:63], v[120:123], v[132:135], v[48:63]
	v_add_f32_e32 v80, v94, v80
	v_add_f32_e32 v80, v95, v80
	v_add_f32_e32 v82, 0, v80
	v_cvt_pk_bf16_f32 v130, v92, v93
	v_cvt_pk_bf16_f32 v131, v94, v95
	v_lshl_add_u64 v[80:81], v[180:181], 0, s[88:89]
	s_add_i32 m0, s42, s39
	s_nop 0
	global_load_lds_dwordx4 v[80:81], off
	s_mov_b64 s[20:21], 0x4000
	v_lshl_add_u64 v[182:183], v[182:183], 0, s[20:21]
	s_add_i32 m0, s44, s35
	s_nop 0
	global_load_lds_dwordx4 v[182:183], off
	v_add_f32_e32 v184, v184, v82
	s_waitcnt lgkmcnt(14)
	v_mfma_f32_32x32x16_bf16 v[0:15], v[148:151], v[116:119], v[0:15]
	v_exp_f32_e32 v64, v64
	v_exp_f32_e32 v65, v65
	v_exp_f32_e32 v66, v66
	v_exp_f32_e32 v67, v67
	s_waitcnt lgkmcnt(12)
	v_mfma_f32_32x32x16_bf16 v[16:31], v[148:151], v[112:115], v[16:31]
	v_exp_f32_e32 v68, v68
	v_exp_f32_e32 v69, v69
	v_exp_f32_e32 v70, v70
	v_exp_f32_e32 v71, v71
	v_add_u32_e32 v92, s44, v225
	ds_read_b128 v[80:83], v92
	ds_read_b128 v[164:167], v92 offset:512
	s_waitcnt lgkmcnt(12)
	v_mfma_f32_32x32x16_bf16 v[0:15], v[144:147], v[96:99], v[0:15]
	v_exp_f32_e32 v72, v72
	v_exp_f32_e32 v73, v73
	v_exp_f32_e32 v74, v74
	v_exp_f32_e32 v75, v75
	ds_read_b128 v[168:171], v92 offset:2048
	ds_read_b128 v[160:163], v92 offset:2560
	s_waitcnt lgkmcnt(12)
	v_mfma_f32_32x32x16_bf16 v[16:31], v[144:147], v[100:103], v[16:31]
	v_exp_f32_e32 v76, v76
	v_exp_f32_e32 v77, v77
	v_exp_f32_e32 v78, v78
	v_exp_f32_e32 v79, v79
	ds_read_b128 v[124:127], v92 offset:4096
	ds_read_b128 v[120:123], v92 offset:4608
	s_waitcnt lgkmcnt(12)
	v_mfma_f32_32x32x16_bf16 v[0:15], v[136:139], v[104:107], v[0:15]
	v_exp_f32_e32 v48, v48
	v_exp_f32_e32 v49, v49
	v_exp_f32_e32 v50, v50
	v_exp_f32_e32 v51, v51
	ds_read_b128 v[116:119], v92 offset:6144
	ds_read_b128 v[112:115], v92 offset:6656
	s_waitcnt lgkmcnt(12)
	v_mfma_f32_32x32x16_bf16 v[16:31], v[136:139], v[108:111], v[16:31]
	v_exp_f32_e32 v52, v52
	v_exp_f32_e32 v53, v53
	v_exp_f32_e32 v54, v54
	v_exp_f32_e32 v55, v55
	s_waitcnt lgkmcnt(10)
	v_mfma_f32_32x32x16_bf16 v[0:15], v[128:131], v[84:87], v[0:15]
	v_exp_f32_e32 v56, v56
	v_exp_f32_e32 v57, v57
	v_exp_f32_e32 v58, v58
	v_exp_f32_e32 v59, v59
	s_waitcnt lgkmcnt(8)
	v_mfma_f32_32x32x16_bf16 v[16:31], v[128:131], v[88:91], v[16:31]
	v_exp_f32_e32 v60, v60
	v_exp_f32_e32 v61, v61
	v_exp_f32_e32 v62, v62
	v_exp_f32_e32 v63, v63
	s_waitcnt vmcnt(2) lgkmcnt(0)
	s_barrier
	s_add_i32 s20, s44, 0x2000
	s_cmpk_lg_i32 s44, 0x4000
	s_cselect_b32 s21, s20, 0
	s_add_i32 s41, s41, 2
	s_mov_b64 s[30:31], 0x4000
	s_cmp_lt_u32 s41, 57
	v_lshl_add_u64 v[180:181], v[180:181], 0, s[30:31]
	s_cbranch_scc0 .LBB0_401
	s_mov_b32 s20, s42
	s_mov_b32 s43, s44
	s_mov_b32 s42, s21
	s_branch .Lattn_fast_top
